# residual GEMM phases: split-K sample units run before the prompt tile (flag s100 two-pass flow)
# baseline (speedup 1.0000x reference)
; template <class Epi, class Sched>
; __device__ __forceinline__ void gemm_phase(LAS unsigned char* lds, const Gemm g, const Sched& S, const Epi& E, const Ids I) {
;     const int tid_local = make_tid(I.wv);
;     const int tid = TID, wid = __builtin_amdgcn_readfirstlane(tid >> 6), lane = tid & 63, wr = wid >> 2, wc = wid & 3, fr = lane & 15, fq = lane >> 4;
;     const int K = g.ld, nt = g.K / BK;
;     unsigned voffA[2], voffB[2];
; #pragma unroll
;     for (int i = 0; i < 2; ++i) { int R, C; stage_rc(tid * 16 + i * 8192, R, C); voffA[i] = (unsigned)(R * K + C) * 2u; voffB[i] = (unsigned)(R * K + C) * 2u; }
;     const size_t kstep = (size_t)(BK * 2);
;     const size_t hstep = (size_t)HALF * K * 2;
;     const size_t tstep = 2 * hstep;
;     const unsigned ldsw = (unsigned)wid * 1024u;
;     const int aoff = lds_byte(wr * 64 + fr, fq * 8), boff = lds_byte(wc * 32 + fr, fq * 8);
;     ...
;     Unit cur, nxt; int ui = 0;
;     if (!S.next(0, cur)) return;
;     f32x4 acc[2][2][4][2];
; #pragma unroll
;     for (int a = 0; a < 2; ++a)
; #pragma unroll
;         for (int b = 0; b < 2; ++b)
; #pragma unroll
;             for (int m = 0; m < 4; ++m)
; #pragma unroll
;                 for (int n = 0; n < 2; ++n) acc[a][b][m][n] = (f32x4){0.f, 0.f, 0.f, 0.f};
;     bf16x8 At[4][2], B0[2][2], B1[2][2];
;     const char* cA = (const char*)g.A + (size_t)cur.pm * tstep + cur.kb; const char* cB = (const char*)g.Bt + (size_t)cur.pn * tstep + cur.kb;
;     PG8_STAGE(PG8_SB(0, 0), cB, voffB); PG8_STAGE(PG8_SA(0, 0), cA, voffA); PG8_STAGE(PG8_SB(0, 1), cB + hstep, voffB); PG8_STAGE(PG8_SA(0, 1), cA + hstep, voffA);
;     if (wr == 1) PG8_BAR;
;     PG8_WAIT_V(4); PG8_BAR;
; __global__ void __launch_bounds__(512) mega(Params Pval) {
;     ...
;                 const int gk = sub == 2 ? 2 : (sub == 8 ? 5 : 8);
;                 const float scl = sub == 8 ? 1.0f : 0.5f; const int Kd = sub == 8 ? 1024 : FF;
;                 EpiResid E{P->out, modl + gk * 1024, scl};
;                 const bf16_t* A = (const bf16_t*)(ws + (sub == 8 ? WS_HB : WS_R1)); const bf16_t* Bt = (const bf16_t*)(ws + (sub == 2 ? WS_WD1 : (sub == 8 ? WS_WOUT : WS_WD2)));
;                 run_gemm(lds, A, Bt, MTP, 1024, Kd, E, I);
;                 EpiPartial EA{(float*)(ws + WS_R2)};
;                 run_gemm_splitk(lds, A + (size_t)MTP * Kd, Bt, MTS, 1024, Kd, 256, EA, I);
.LBB0_358:
	s_and_b64 vcc, exec, s[14:15]
	s_cbranch_vccz .LBB0_394
	s_mov_b32 s100, 0
.Lres_pre:
	s_cmp_eq_u32 s30, 8
	s_cselect_b64 s[6:7], -1, 0
	s_cmp_eq_u32 s30, 2
	s_cselect_b64 s[4:5], -1, 0
	s_and_b64 s[0:1], s[6:7], exec
	s_movk_i32 s0, 0x400
	s_cselect_b32 s23, s0, 0xb00
	s_mov_b32 s0, 0x3294000
	s_cselect_b32 s0, s0, 0x5394000
	s_add_u32 s0, s86, s0
	s_addc_u32 s1, s87, 0
	s_and_b64 s[8:9], s[6:7], exec
	s_mov_b32 s3, 0x1604000
	s_cselect_b32 s3, s3, 0x2304000
	s_and_b64 s[8:9], s[4:5], exec
	s_cselect_b32 s3, 0xb04000, s3
	s_mov_b64 s[52:53], s[20:21]
	s_add_u32 s20, s86, s3
	v_mbcnt_lo_u32_b32 v18, -1, 0
	v_mbcnt_hi_u32_b32 v18, -1, v18
	s_addc_u32 s21, s87, 0
	v_add_u32_e32 v0, s62, v18
	s_lshl_b32 s54, s23, 8
	s_lshl_b32 s22, s23, 9
	s_andn2_b64 vcc, exec, s[42:43]
	v_readfirstlane_b32 s3, v0
	s_cmp_eq_u32 s100, 2
	s_cbranch_scc1 .Lres_p
	s_cbranch_vccnz .LBB0_379
	s_mov_b32 s100, 1
	s_branch .LBB0_379
.Lres_p:
	v_lshlrev_b32_e32 v1, 4, v0
	v_add_u32_e32 v2, 0x2000, v1
	v_ashrrev_i32_e32 v3, 31, v2
	v_lshrrev_b32_e32 v3, 22, v3
	v_add_u32_e32 v3, v2, v3
	v_ashrrev_i32_e32 v3, 10, v3
	v_mul_i32_i24_e32 v4, 0x400, v3
	v_sub_u32_e32 v2, v2, v4
	v_lshrrev_b32_e32 v4, 4, v2
	v_bitop3_b32 v2, v4, v2, 32 bitop3:0x6c
	s_ashr_i32 s8, s3, 6
	v_ashrrev_i32_e32 v4, 31, v2
	s_waitcnt lgkmcnt(0)
	v_readlane_b32 s10, v254, 14
	s_ashr_i32 s9, s3, 8
	s_lshl_b32 s24, s8, 10
	s_lshl_b32 s14, s47, 5
	v_lshrrev_b32_e32 v4, 26, v4
	v_readlane_b32 s11, v254, 15
	s_mul_i32 s15, s47, 33
	v_add_u32_e32 v4, v2, v4
	s_and_b64 s[10:11], s[10:11], exec
	v_ashrrev_i32_e32 v5, 6, v4
	v_and_b32_e32 v4, 0xc0, v4
	s_cselect_b32 s10, s15, s14
	v_readlane_b32 s11, v254, 28
	v_sub_u32_e32 v2, v2, v4
	s_add_i32 s10, s10, s11
	v_ashrrev_i16_sdwa v2, v237, sext(v2) dst_sel:DWORD dst_unused:UNUSED_PAD src0_sel:DWORD src1_sel:BYTE_0
	s_ashr_i32 s11, s10, 31
	v_bfe_i32 v14, v2, 0, 16
	v_bfe_i32 v2, v0, 27, 1
	s_lshr_b32 s11, s11, 27
	v_lshrrev_b32_e32 v2, 22, v2
	s_add_i32 s11, s10, s11
	v_add_u32_e32 v2, v1, v2
	s_ashr_i32 s14, s11, 5
	s_and_b32 s11, s11, 0xffe0
	v_and_b32_e32 v2, 0xfffffc00, v2
	s_sub_i32 s10, s10, s11
	v_sub_u32_e32 v1, v1, v2
	s_bfe_i32 s11, s10, 0x80000
	v_lshlrev_b32_e32 v6, 3, v3
	v_lshrrev_b32_e32 v2, 4, v1
	v_ashrrev_i32_e32 v4, 31, v0
	s_bfe_u32 s11, s11, 0x3000c
	v_and_b32_e32 v6, 0x7ffffff0, v6
	v_bitop3_b32 v1, v2, v1, 32 bitop3:0x6c
	v_lshrrev_b32_e32 v4, 26, v4
	s_add_i32 s11, s10, s11
	v_add_u32_e32 v5, v5, v6
	v_lshlrev_b32_e32 v3, 5, v3
	v_ashrrev_i32_e32 v2, 31, v1
	v_add_u32_e32 v0, v0, v4
	s_bfe_i32 s15, s11, 0x80000
	s_and_b32 s11, s11, 0xf8
	v_mul_lo_u32 v12, v5, s23
	v_and_b32_e32 v13, 32, v3
	v_lshrrev_b32_e32 v2, 26, v2
	v_ashrrev_i32_e32 v0, 6, v0
	s_sub_i32 s10, s10, s11
	v_or_b32_e32 v3, v12, v13
	v_add_u32_e32 v2, v1, v2
	v_lshlrev_b32_e32 v4, 3, v0
	s_lshl_b32 s14, s14, 3
	s_sext_i32_i16 s15, s15
	s_sext_i32_i8 s10, s10
	v_add_lshl_u32 v128, v3, v14, 1
	v_ashrrev_i32_e32 v3, 6, v2
	v_and_b32_e32 v4, 0x7ffffff0, v4
	v_and_b32_e32 v2, 0xc0, v2
	s_add_i32 s40, s14, s10
	s_ashr_i32 s14, s15, 3
	v_add_u32_e32 v3, v3, v4
	v_lshlrev_b32_e32 v0, 5, v0
	v_sub_u32_e32 v1, v1, v2
	s_lshr_b32 s18, s15, 3
	s_mul_hi_i32 s15, s22, s14
	s_mul_i32 s14, s22, s14
	v_mul_lo_u32 v15, v3, s23
	v_and_b32_e32 v16, 32, v0
	v_ashrrev_i16_sdwa v1, v237, sext(v1) dst_sel:DWORD dst_unused:UNUSED_PAD src0_sel:DWORD src1_sel:BYTE_0
	s_add_u32 s16, s20, s14
	s_mov_b32 s50, s25
	v_or_b32_e32 v0, v15, v16
	v_bfe_i32 v17, v1, 0, 16
	s_addc_u32 s17, s21, s15
	s_add_i32 s25, s24, 0
	v_add_lshl_u32 v144, v0, v17, 1
	s_add_i32 m0, s25, 0x10000
	s_mul_i32 s11, s22, s40
	global_load_lds_dwordx4 v144, s[16:17]
	s_add_i32 m0, s25, 0x12000
	s_mul_hi_i32 s10, s22, s40
	s_add_u32 s14, s0, s11
	global_load_lds_dwordx4 v128, s[16:17]
	s_addc_u32 s15, s1, s10
	s_mov_b32 m0, s25
	s_add_i32 s26, s25, 0x2000
	global_load_lds_dwordx4 v144, s[14:15]
	s_mov_b32 m0, s26
	s_add_u32 s30, s16, s54
	global_load_lds_dwordx4 v128, s[14:15]
	s_addc_u32 s31, s17, 0
	s_add_i32 m0, s25, 0x14000
	v_mov_b32_e32 v129, v145
	global_load_lds_dwordx4 v144, s[30:31]
	s_add_i32 m0, s25, 0x16000
	s_add_u32 s10, s14, s54
	s_addc_u32 s11, s15, 0
	s_add_i32 s27, s25, 0x4000
	global_load_lds_dwordx4 v128, s[30:31]
	s_mov_b32 m0, s27
	s_add_i32 s28, s25, 0x6000
	global_load_lds_dwordx4 v144, s[10:11]
	s_mov_b32 m0, s28
	v_lshl_add_u64 v[10:11], s[16:17], 0, v[144:145]
	global_load_lds_dwordx4 v128, s[10:11]
	s_load_dwordx2 s[10:11], s[88:89], 0x140
	v_lshl_add_u64 v[8:9], s[16:17], 0, v[128:129]
	v_lshl_add_u64 v[6:7], s[14:15], 0, v[144:145]
	v_lshl_add_u64 v[4:5], s[14:15], 0, v[128:129]
	v_lshl_add_u64 v[2:3], s[30:31], 0, v[144:145]
	s_cmp_lg_u32 s9, 1
	v_lshl_add_u64 v[0:1], s[30:31], 0, v[128:129]
	s_cbranch_scc1 .LBB0_362
	s_barrier

; #define PG8_WAIT_V(n) asm volatile("s_waitcnt vmcnt(" #n ")" ::: "memory")
; #define PG8_BAR __builtin_amdgcn_s_barrier()
; template <class Epi, class Sched>
; __device__ __forceinline__ void gemm_phase(LAS unsigned char* lds, const Gemm g, const Sched& S, const Epi& E, const Ids I) {
;     ...
;     PG8_WAIT_V(0);
;     if (wr == 0) PG8_BAR;
;     PG8_BAR;
.LBB0_378:
	s_mov_b32 s25, s50
	v_readlane_b32 s27, v254, 47
	s_barrier
	s_cmp_eq_u32 s100, 2
	s_cbranch_scc1 .LBB0_393

; __global__ void __launch_bounds__(512) mega(Params Pval) {
;     ...
;                 run_gemm(lds, A, Bt, MTP, 1024, Kd, E, I);
;                 EpiPartial EA{(float*)(ws + WS_R2)};
;                 run_gemm_splitk(lds, A + (size_t)MTP * Kd, Bt, MTS, 1024, Kd, 256, EA, I);
.LBB0_393:
	s_mov_b64 s[36:37], 0
	s_mov_b64 s[20:21], s[52:53]
	s_cmp_eq_u32 s100, 1
	s_cbranch_scc0 .Lres_cont
	s_mov_b32 s100, 2
	s_branch .Lres_pre
.Lres_cont:
.LBB0_394:
	s_mov_b64 s[4:5], 0
	s_and_b64 vcc, exec, s[20:21]
	s_cbranch_vccz .LBB0_396
	s_cmp_gt_i32 s30, 0
	s_mov_b64 s[4:5], -1
	s_cselect_b64 s[36:37], -1, 0
